# phase-0 in-projection weight transpose: 16 predicated row loads of a tile issued together with counted waits (was 16 serial load/wait/LDS-write round trips)
# baseline (speedup 1.0000x reference)
; DI void transpose_tile(const float* __restrict__ src, int ldsrc, u16* __restrict__ dst, int Kd, int k0, int n0, bool mapped, char* smem) {
;     ...
;   const int sc = mapped ? map_win(nd) : nd;
; #pragma unroll 4
;   for (int i = 0; i < 16; ++i) {
;     int k = (tid >> 6) + 4 * i;
;     float v = (sc >= 0) ? src[(size_t)(k0 + k) * ldsrc + sc] : 0.f;
;     s[k * 65 + nn] = v;
;   }
.LBB0_87:
	v_mov_b32_e32 v86, 0
	v_mov_b32_e32 v87, 0
	v_mov_b32_e32 v88, 0
	v_mov_b32_e32 v89, 0
	v_mov_b32_e32 v90, 0
	v_mov_b32_e32 v91, 0
	v_mov_b32_e32 v92, 0
	v_mov_b32_e32 v93, 0
	v_mov_b32_e32 v94, 0
	v_mov_b32_e32 v95, 0
	v_mov_b32_e32 v96, 0
	v_mov_b32_e32 v97, 0
	v_mov_b32_e32 v98, 0
	v_mov_b32_e32 v99, 0
	v_mov_b32_e32 v100, 0
	v_mov_b32_e32 v101, 0
	s_and_saveexec_b64 s[26:27], vcc
	v_lshl_add_u64 v[34:35], v[32:33], 0, s[24:25]
	global_load_dword v86, v[34:35], off
	v_lshl_add_u64 v[34:35], v[30:31], 0, s[24:25]
	global_load_dword v87, v[34:35], off
	v_lshl_add_u64 v[34:35], v[28:29], 0, s[24:25]
	global_load_dword v88, v[34:35], off
	v_lshl_add_u64 v[34:35], v[26:27], 0, s[24:25]
	global_load_dword v89, v[34:35], off
	s_add_u32 s24, s24, 0x30600
	s_addc_u32 s25, s25, 0
	v_lshl_add_u64 v[34:35], v[32:33], 0, s[24:25]
	global_load_dword v90, v[34:35], off
	v_lshl_add_u64 v[34:35], v[30:31], 0, s[24:25]
	global_load_dword v91, v[34:35], off
	v_lshl_add_u64 v[34:35], v[28:29], 0, s[24:25]
	global_load_dword v92, v[34:35], off
	v_lshl_add_u64 v[34:35], v[26:27], 0, s[24:25]
	global_load_dword v93, v[34:35], off
	s_add_u32 s24, s24, 0x30600
	s_addc_u32 s25, s25, 0
	v_lshl_add_u64 v[34:35], v[32:33], 0, s[24:25]
	global_load_dword v94, v[34:35], off
	v_lshl_add_u64 v[34:35], v[30:31], 0, s[24:25]
	global_load_dword v95, v[34:35], off
	v_lshl_add_u64 v[34:35], v[28:29], 0, s[24:25]
	global_load_dword v96, v[34:35], off
	v_lshl_add_u64 v[34:35], v[26:27], 0, s[24:25]
	global_load_dword v97, v[34:35], off
	s_add_u32 s24, s24, 0x30600
	s_addc_u32 s25, s25, 0
	v_lshl_add_u64 v[34:35], v[32:33], 0, s[24:25]
	global_load_dword v98, v[34:35], off
	v_lshl_add_u64 v[34:35], v[30:31], 0, s[24:25]
	global_load_dword v99, v[34:35], off
	v_lshl_add_u64 v[34:35], v[28:29], 0, s[24:25]
	global_load_dword v100, v[34:35], off
	v_lshl_add_u64 v[34:35], v[26:27], 0, s[24:25]
	global_load_dword v101, v[34:35], off
	s_add_u32 s24, s24, 0x30600
	s_addc_u32 s25, s25, 0
	s_or_b64 exec, exec, s[26:27]
	s_waitcnt vmcnt(15)
	ds_write_b32 v2, v86
	s_waitcnt vmcnt(14)
	ds_write_b32 v2, v87 offset:1040
	s_waitcnt vmcnt(13)
	ds_write_b32 v2, v88 offset:2080
	s_waitcnt vmcnt(12)
	ds_write_b32 v2, v89 offset:3120
	v_add_u32_e32 v2, 0x1040, v2
	s_waitcnt vmcnt(11)
	ds_write_b32 v2, v90
	s_waitcnt vmcnt(10)
	ds_write_b32 v2, v91 offset:1040
	s_waitcnt vmcnt(9)
	ds_write_b32 v2, v92 offset:2080
	s_waitcnt vmcnt(8)
	ds_write_b32 v2, v93 offset:3120
	v_add_u32_e32 v2, 0x1040, v2
	s_waitcnt vmcnt(7)
	ds_write_b32 v2, v94
	s_waitcnt vmcnt(6)
	ds_write_b32 v2, v95 offset:1040
	s_waitcnt vmcnt(5)
	ds_write_b32 v2, v96 offset:2080
	s_waitcnt vmcnt(4)
	ds_write_b32 v2, v97 offset:3120
	v_add_u32_e32 v2, 0x1040, v2
	s_waitcnt vmcnt(3)
	ds_write_b32 v2, v98
	s_waitcnt vmcnt(2)
	ds_write_b32 v2, v99 offset:1040
	s_waitcnt vmcnt(1)
	ds_write_b32 v2, v100 offset:2080
	s_waitcnt vmcnt(0)
	ds_write_b32 v2, v101 offset:3120
	v_add_u32_e32 v2, 0x1040, v2
